# attention: the two in-loop QK^T blocks software-pipelined (next d0 fragment reads issued before the current MFMAs, alternate fragment registers, lgkmcnt(3))
# baseline (speedup 1.0000x reference)
; __device__ __forceinline__ void finishSM(f32x16& p0, f32x16& p1, float alpha, float& l_reg, bf16x8& pa0, bf16x8& pa1, bf16x8& pa2, bf16x8& pa3) {
; #pragma unroll
;     for (int r = 0; r < 16; ++r) p1[r] = __builtin_amdgcn_exp2f(p1[r]);
;     float ps = 0;
; #pragma unroll
;     for (int r = 0; r < 16; ++r) ps += p0[r];
; #pragma unroll
;     for (int r = 0; r < 16; ++r) ps += p1[r];
;     { auto rr = __builtin_amdgcn_permlane32_swap(__float_as_uint(ps), __float_as_uint(ps), false, false);
;       ps = __uint_as_float(rr[0]) + __uint_as_float(rr[1]); }
;     l_reg = l_reg * alpha + ps;
;     ...
;     PK4(p0, 0, pa0); PK4(p0, 8, pa1); PK4(p1, 0, pa2); PK4(p1, 8, pa3);
; template <int KB>
; __device__ __forceinline__ void qkt(f32x16& p0, f32x16& p1, const char* K_lds, const float* cb_l, int r32, int hi, qlds_t qL) {
;     { const float* cbt = cb_l + KB * 64 + 4 * hi;
; #pragma unroll
;       for (int g4 = 0; g4 < 4; ++g4) { const f32x4 b0 = *(const f32x4*)(cbt + 8 * g4), b1 = *(const f32x4*)(cbt + 32 + 8 * g4);
; #pragma unroll
;           for (int i = 0; i < 4; ++i) { p0[4 * g4 + i] = b0[i]; p1[4 * g4 + i] = b1[i]; } } }
;     const char* kb[4];
; #pragma unroll
;     for (int dd = 0; dd < 4; ++dd) kb[dd] = K_lds + KB * SHM_K + KSWZ(r32, (dd * 16 + hi * 8) * 2);
; #pragma unroll
;     for (int d0 = 0; d0 < 8; ++d0) { const char* a = kb[d0 & 3] + (d0 >> 2) * 128;
;         bf16x8 b0 = *reinterpret_cast<const bf16x8*>(a);
;         bf16x8 b1 = *reinterpret_cast<const bf16x8*>(a + 32 * 256);
;         const bf16x8 q = qL[d0 * 64];
;         p0 = __builtin_amdgcn_mfma_f32_32x32x16_bf16(b0, q, p0, 0, 0, 0);
;         p1 = __builtin_amdgcn_mfma_f32_32x32x16_bf16(b1, q, p1, 0, 0, 0); }
.LBB0_500:
	v_add_u32_e32 v92, 0x10900, v183
	ds_read_b128 v[64:67], v92
	ds_read_b128 v[68:71], v92 offset:32
	ds_read_b128 v[80:83], v92 offset:128
	ds_read_b128 v[84:87], v92 offset:160
	ds_read_b128 v[72:75], v92 offset:64
	ds_read_b128 v[88:91], v92 offset:192
	ds_read_b128 v[76:79], v92 offset:96
	ds_read_b128 v[92:95], v92 offset:224
	s_waitcnt vmcnt(4)
	ds_read_b128 v[112:115], v182 offset:49152
	s_waitcnt vmcnt(2)
	ds_read_b128 v[116:119], v182 offset:57344
	ds_read_b128 v[120:123], v167
	ds_read_b128 v[228:231], v181 offset:49152
	ds_read_b128 v[232:235], v181 offset:57344
	ds_read_b128 v[242:245], v167 offset:1024
	v_exp_f32_e32 v102, v102
	v_exp_f32_e32 v103, v103
	v_exp_f32_e32 v100, v100
	v_exp_f32_e32 v101, v101
	s_waitcnt lgkmcnt(3)
	v_mfma_f32_32x32x16_bf16 v[80:95], v[116:119], v[120:123], v[80:95]
	v_exp_f32_e32 v98, v98
	v_exp_f32_e32 v99, v99
	v_exp_f32_e32 v96, v96
	v_exp_f32_e32 v97, v97
	v_mfma_f32_32x32x16_bf16 v[64:79], v[112:115], v[120:123], v[64:79]
	ds_read_b128 v[112:115], v180 offset:49152
	ds_read_b128 v[116:119], v180 offset:57344
	ds_read_b128 v[120:123], v167 offset:2048
	s_waitcnt lgkmcnt(3)
	v_mfma_f32_32x32x16_bf16 v[80:95], v[232:235], v[242:245], v[80:95]
	v_mfma_f32_32x32x16_bf16 v[64:79], v[228:231], v[242:245], v[64:79]
	ds_read_b128 v[228:231], v179 offset:49152
	ds_read_b128 v[232:235], v179 offset:57344
	ds_read_b128 v[242:245], v167 offset:3072
	s_waitcnt lgkmcnt(3)
	v_mfma_f32_32x32x16_bf16 v[80:95], v[116:119], v[120:123], v[80:95]
	v_mfma_f32_32x32x16_bf16 v[64:79], v[112:115], v[120:123], v[64:79]
	ds_read_b128 v[112:115], v182 offset:49280
	ds_read_b128 v[116:119], v182 offset:57472
	ds_read_b128 v[120:123], v167 offset:4096
	s_waitcnt lgkmcnt(3)
	v_mfma_f32_32x32x16_bf16 v[80:95], v[232:235], v[242:245], v[80:95]
	v_mfma_f32_32x32x16_bf16 v[64:79], v[228:231], v[242:245], v[64:79]
	ds_read_b128 v[228:231], v181 offset:49280
	ds_read_b128 v[232:235], v181 offset:57472
	ds_read_b128 v[242:245], v167 offset:5120
	s_waitcnt lgkmcnt(3)
	v_mfma_f32_32x32x16_bf16 v[80:95], v[116:119], v[120:123], v[80:95]
	v_mfma_f32_32x32x16_bf16 v[64:79], v[112:115], v[120:123], v[64:79]
	ds_read_b128 v[112:115], v180 offset:49280
	ds_read_b128 v[116:119], v180 offset:57472
	ds_read_b128 v[120:123], v167 offset:6144
	s_waitcnt lgkmcnt(3)
	v_mfma_f32_32x32x16_bf16 v[80:95], v[232:235], v[242:245], v[80:95]
	v_mfma_f32_32x32x16_bf16 v[64:79], v[228:231], v[242:245], v[64:79]
	ds_read_b128 v[228:231], v179 offset:49280
	ds_read_b128 v[232:235], v179 offset:57472
	ds_read_b128 v[242:245], v167 offset:7168
	s_waitcnt lgkmcnt(3)
	v_mfma_f32_32x32x16_bf16 v[80:95], v[116:119], v[120:123], v[80:95]
	v_mfma_f32_32x32x16_bf16 v[64:79], v[112:115], v[120:123], v[64:79]
	s_waitcnt lgkmcnt(0)
	v_mfma_f32_32x32x16_bf16 v[80:95], v[232:235], v[242:245], v[80:95]
	v_exp_f32_e32 v118, v104
	v_add_f32_e32 v104, 0, v219
	v_add_f32_e32 v104, v221, v104
	v_add_f32_e32 v104, v217, v104
	v_add_f32_e32 v104, v220, v104
	v_add_f32_e32 v104, v215, v104
	v_add_f32_e32 v104, v218, v104
	v_add_f32_e32 v104, v214, v104
	v_add_f32_e32 v104, v216, v104
	v_add_f32_e32 v104, v209, v104
	v_add_f32_e32 v104, v212, v104
	v_add_f32_e32 v104, v207, v104
	v_add_f32_e32 v104, v210, v104
	v_mfma_f32_32x32x16_bf16 v[64:79], v[228:231], v[242:245], v[64:79]
	v_exp_f32_e32 v112, v106
	v_add_f32_e32 v104, v137, v104
	v_exp_f32_e32 v113, v107
	v_add_f32_e32 v104, v213, v104
	v_exp_f32_e32 v114, v108
	v_add_f32_e32 v104, v208, v104
	v_exp_f32_e32 v115, v109
	v_add_f32_e32 v104, v211, v104
	v_exp_f32_e32 v116, v110
	v_add_f32_e32 v104, v112, v104
	v_exp_f32_e32 v117, v111
	v_add_f32_e32 v104, v113, v104
	v_add_f32_e32 v104, v114, v104
	v_exp_f32_e32 v119, v105
	v_add_f32_e32 v104, v115, v104
	v_add_f32_e32 v104, v116, v104
	v_add_f32_e32 v104, v117, v104
	v_add_f32_e32 v104, v118, v104
	v_add_f32_e32 v104, v119, v104
	v_add_f32_e32 v104, v102, v104
	v_add_f32_e32 v104, v103, v104
	v_add_f32_e32 v104, v100, v104
	v_add_f32_e32 v104, v101, v104
	v_add_f32_e32 v104, v98, v104
	v_add_f32_e32 v104, v99, v104
	v_add_f32_e32 v104, v96, v104
	v_add_f32_e32 v191, v97, v104
	v_mov_b32_e32 v197, v191
	s_nop 1
	v_permlane32_swap_b32_e32 v191, v197
	v_cvt_pk_bf16_f32 v104, v219, v221
	v_cvt_pk_bf16_f32 v105, v217, v220
	v_cvt_pk_bf16_f32 v106, v215, v218
	v_cvt_pk_bf16_f32 v107, v214, v216
	v_cvt_pk_bf16_f32 v108, v209, v212
	v_cvt_pk_bf16_f32 v109, v207, v210
	v_cvt_pk_bf16_f32 v110, v137, v213
	v_cvt_pk_bf16_f32 v111, v208, v211
	v_cvt_pk_bf16_f32 v112, v112, v113
	v_cvt_pk_bf16_f32 v113, v114, v115
	v_cvt_pk_bf16_f32 v114, v116, v117
	v_cvt_pk_bf16_f32 v115, v118, v119
	v_cvt_pk_bf16_f32 v116, v102, v103
	v_cvt_pk_bf16_f32 v117, v100, v101
	v_cvt_pk_bf16_f32 v118, v98, v99
	v_cvt_pk_bf16_f32 v119, v96, v97
	s_nop 0
	v_permlane32_swap_b32_e32 v104, v106
	v_permlane32_swap_b32_e32 v105, v107
	v_permlane32_swap_b32_e32 v108, v110
	v_permlane32_swap_b32_e32 v109, v111
	v_permlane32_swap_b32_e32 v112, v114
	v_permlane32_swap_b32_e32 v113, v115
	v_permlane32_swap_b32_e32 v116, v118
	v_permlane32_swap_b32_e32 v117, v119
	s_add_i32 s90, s13, 1
	s_ashr_i32 s91, s90, 31
	s_lshl_b64 s[40:41], s[90:91], 8
	s_add_u32 s56, s48, s40
	s_addc_u32 s57, s49, s41
	s_add_u32 s40, s46, s40
	v_lshl_add_u64 v[96:97], s[56:57], 0, v[138:139]
	s_addc_u32 s41, s47, s41
	v_add_co_u32_e32 v100, vcc, s60, v96
	v_lshl_add_u64 v[120:121], s[40:41], 0, v[138:139]
	s_nop 0
	v_addc_co_u32_e32 v101, vcc, 0, v97, vcc
	v_add_co_u32_e32 v122, vcc, s60, v120
	global_load_dwordx4 v[96:99], v[96:97], off
	s_nop 0
	global_load_dwordx4 v[100:103], v[100:101], off
	v_addc_co_u32_e32 v123, vcc, 0, v121, vcc
	global_load_dwordx4 v[140:143], v[120:121], off
	global_load_dwordx4 v[144:147], v[122:123], off
	v_lshl_add_u64 v[120:121], s[90:91], 2, v[168:169]
	global_load_dword v207, v[120:121], off
	ds_read_b64_tr_b16 v[120:121], v177 offset:0
	ds_read_b64_tr_b16 v[122:123], v177 offset:0x800
	s_waitcnt vmcnt(6)
; __device__ __forceinline__ void mask_tile(f32x16& p0, f32x16& p1, int dq, unsigned W) {
;     const float NEG = -__builtin_inff();
; #pragma unroll
;     for (int r = 0; r < 16; ++r) {
;         const int c = (r & 3) + 8 * (r >> 2);
;         if ((unsigned)(dq - c) >= W) p0[r] = NEG;
;         if ((unsigned)(dq - c - 32) >= W) p1[r] = NEG;
;     }
; template <int VB>
; __device__ __forceinline__ void pv_tile(f32x16* o, int vb0, bf16x8 pa0, bf16x8 pa1, bf16x8 pa2, bf16x8 pa3) {
;     ...
;     PV_D0(0); PV_D0(1); PV_D0(2); PV_D0(3);
	ds_read_b64_tr_b16 v[124:125], v177 offset:0x1000
	ds_read_b64_tr_b16 v[126:127], v177 offset:0x1800
	ds_read_b64_tr_b16 v[128:129], v177 offset:0x2000
	ds_read_b64_tr_b16 v[130:131], v177 offset:0x2800
	ds_read_b64_tr_b16 v[132:133], v177 offset:0x3000
	ds_read_b64_tr_b16 v[134:135], v177 offset:0x3800
	s_waitcnt lgkmcnt(0)
	v_mfma_f32_32x32x16_bf16 v[48:63], v[104:107], v[120:123], v[48:63]
	ds_read_b64_tr_b16 v[120:121], v177 offset:0x200
	ds_read_b64_tr_b16 v[122:123], v177 offset:0xa00
	v_mfma_f32_32x32x16_bf16 v[48:63], v[108:111], v[124:127], v[48:63]
	ds_read_b64_tr_b16 v[124:125], v177 offset:0x1200
	ds_read_b64_tr_b16 v[126:127], v177 offset:0x1a00
	v_mfma_f32_32x32x16_bf16 v[48:63], v[112:115], v[128:131], v[48:63]
	ds_read_b64_tr_b16 v[128:129], v177 offset:0x2200
	ds_read_b64_tr_b16 v[130:131], v177 offset:0x2a00
	v_mfma_f32_32x32x16_bf16 v[48:63], v[116:119], v[132:135], v[48:63]
	ds_read_b64_tr_b16 v[132:133], v177 offset:0x3200
	ds_read_b64_tr_b16 v[134:135], v177 offset:0x3a00
	s_waitcnt lgkmcnt(0)
	v_mfma_f32_32x32x16_bf16 v[32:47], v[104:107], v[120:123], v[32:47]
	ds_read_b64_tr_b16 v[120:121], v177 offset:0x400
	ds_read_b64_tr_b16 v[122:123], v177 offset:0xc00
	v_mfma_f32_32x32x16_bf16 v[32:47], v[108:111], v[124:127], v[32:47]
	ds_read_b64_tr_b16 v[124:125], v177 offset:0x1400
	ds_read_b64_tr_b16 v[126:127], v177 offset:0x1c00
	v_mfma_f32_32x32x16_bf16 v[32:47], v[112:115], v[128:131], v[32:47]
	ds_read_b64_tr_b16 v[128:129], v177 offset:0x2400
	ds_read_b64_tr_b16 v[130:131], v177 offset:0x2c00
	v_mfma_f32_32x32x16_bf16 v[32:47], v[116:119], v[132:135], v[32:47]
	ds_read_b64_tr_b16 v[132:133], v177 offset:0x3400
	ds_read_b64_tr_b16 v[134:135], v177 offset:0x3c00
	s_waitcnt lgkmcnt(0)
	v_mfma_f32_32x32x16_bf16 v[16:31], v[104:107], v[120:123], v[16:31]
	ds_read_b64_tr_b16 v[120:121], v177 offset:0x600
	ds_read_b64_tr_b16 v[122:123], v177 offset:0xe00
	v_mfma_f32_32x32x16_bf16 v[16:31], v[108:111], v[124:127], v[16:31]
	ds_read_b64_tr_b16 v[124:125], v177 offset:0x1600
	ds_read_b64_tr_b16 v[126:127], v177 offset:0x1e00
	v_mfma_f32_32x32x16_bf16 v[16:31], v[112:115], v[128:131], v[16:31]
	ds_read_b64_tr_b16 v[128:129], v177 offset:0x2600
	ds_read_b64_tr_b16 v[130:131], v177 offset:0x2e00
	v_mfma_f32_32x32x16_bf16 v[16:31], v[116:119], v[132:135], v[16:31]
	ds_read_b64_tr_b16 v[132:133], v177 offset:0x3600
	ds_read_b64_tr_b16 v[134:135], v177 offset:0x3e00
	s_waitcnt lgkmcnt(0)
	v_mfma_f32_32x32x16_bf16 v[0:15], v[104:107], v[120:123], v[0:15]
	s_sub_i32 s6, s13, 63
	s_cmp_le_i32 s13, s1
	s_cselect_b64 s[40:41], -1, 0
	s_cmp_gt_i32 s6, s92
	s_cselect_b64 s[56:57], -1, 0
	s_and_b64 s[40:41], s[40:41], s[56:57]
	s_and_b64 vcc, exec, s[40:41]
	v_mfma_f32_32x32x16_bf16 v[0:15], v[108:111], v[124:127], v[0:15]
	v_mfma_f32_32x32x16_bf16 v[0:15], v[112:115], v[128:131], v[0:15]
	v_mfma_f32_32x32x16_bf16 v[0:15], v[116:119], v[132:135], v[0:15]
	s_cbranch_vccnz .LBB0_502
	v_add_u32_e32 v104, 0x207b, v190
	v_cmp_gt_u32_e32 vcc, s60, v104
	v_add_u32_e32 v104, 0x5b, v190
	s_nop 0
	v_cndmask_b32_e32 v64, v241, v64, vcc
	v_cmp_lt_u32_e32 vcc, s35, v104
	v_add_u32_e32 v104, 0x7a, v190
	s_nop 0
	v_cndmask_b32_e32 v80, v241, v80, vcc
	v_cmp_lt_u32_e32 vcc, s35, v104
	v_add_u32_e32 v104, 0x5a, v190
	s_nop 0
	v_cndmask_b32_e32 v65, v241, v65, vcc
	v_cmp_lt_u32_e32 vcc, s35, v104
	v_add_u32_e32 v104, 0x79, v190
	s_nop 0
	v_cndmask_b32_e32 v81, v241, v81, vcc
	v_cmp_lt_u32_e32 vcc, s35, v104
	v_add_u32_e32 v104, 0x59, v190
	s_nop 0
	v_cndmask_b32_e32 v66, v241, v66, vcc
	v_cmp_lt_u32_e32 vcc, s35, v104
	v_add_u32_e32 v104, 0x78, v190
	s_nop 0
	v_cndmask_b32_e32 v82, v241, v82, vcc
	v_cmp_lt_u32_e32 vcc, s35, v104
	v_add_u32_e32 v104, 0x58, v190
	s_nop 0
	v_cndmask_b32_e32 v67, v241, v67, vcc
	v_cmp_lt_u32_e32 vcc, s35, v104
	v_add_u32_e32 v104, 0x73, v190
	s_nop 0
	v_cndmask_b32_e32 v83, v241, v83, vcc
	v_cmp_lt_u32_e32 vcc, s35, v104
	v_add_u32_e32 v104, 0x53, v190
	s_nop 0
	v_cndmask_b32_e32 v68, v241, v68, vcc
	v_cmp_lt_u32_e32 vcc, s35, v104
	v_add_u32_e32 v104, 0x72, v190
	s_nop 0
	v_cndmask_b32_e32 v84, v241, v84, vcc
	v_cmp_lt_u32_e32 vcc, s35, v104
	v_add_u32_e32 v104, 0x52, v190
	s_nop 0
	v_cndmask_b32_e32 v69, v241, v69, vcc
	v_cmp_lt_u32_e32 vcc, s35, v104
	v_add_u32_e32 v104, 0x71, v190
	s_nop 0
	v_cndmask_b32_e32 v85, v241, v85, vcc
	v_cmp_lt_u32_e32 vcc, s35, v104
	v_add_u32_e32 v104, 0x51, v190
	s_nop 0
	v_cndmask_b32_e32 v70, v241, v70, vcc
	v_cmp_lt_u32_e32 vcc, s35, v104
	v_add_u32_e32 v104, 0x70, v190
	s_nop 0
	v_cndmask_b32_e32 v86, v241, v86, vcc
	v_cmp_lt_u32_e32 vcc, s35, v104
	v_add_u32_e32 v104, 0x50, v190
	s_nop 0
	v_cndmask_b32_e32 v71, v241, v71, vcc
	v_cmp_lt_u32_e32 vcc, s35, v104
	v_add_u32_e32 v104, 0x6b, v190
	s_nop 0
	v_cndmask_b32_e32 v87, v241, v87, vcc
	v_cmp_lt_u32_e32 vcc, s35, v104
	v_add_u32_e32 v104, 0x4b, v190
	s_nop 0
	v_cndmask_b32_e32 v72, v241, v72, vcc
	v_cmp_lt_u32_e32 vcc, s35, v104
	v_add_u32_e32 v104, 0x6a, v190
	s_nop 0
	v_cndmask_b32_e32 v88, v241, v88, vcc
	v_cmp_lt_u32_e32 vcc, s35, v104
	v_add_u32_e32 v104, 0x4a, v190
	s_nop 0
	v_cndmask_b32_e32 v73, v241, v73, vcc
	v_cmp_lt_u32_e32 vcc, s35, v104
	v_add_u32_e32 v104, 0x69, v190
	s_nop 0
	v_cndmask_b32_e32 v89, v241, v89, vcc
	v_cmp_lt_u32_e32 vcc, s35, v104
	v_add_u32_e32 v104, 0x49, v190
	s_nop 0
	v_cndmask_b32_e32 v74, v241, v74, vcc
	v_cmp_lt_u32_e32 vcc, s35, v104
	v_add_u32_e32 v104, 0x68, v190
	s_nop 0
	v_cndmask_b32_e32 v90, v241, v90, vcc
	v_cmp_lt_u32_e32 vcc, s35, v104
	v_add_u32_e32 v104, 0x48, v190
	s_nop 0
	v_cndmask_b32_e32 v75, v241, v75, vcc
	v_cmp_lt_u32_e32 vcc, s35, v104
	v_add_u32_e32 v104, 0x63, v190
	s_nop 0
	v_cndmask_b32_e32 v91, v241, v91, vcc
	v_cmp_lt_u32_e32 vcc, s35, v104
	v_add_u32_e32 v104, 0x43, v190
	s_nop 0
	v_cndmask_b32_e32 v76, v241, v76, vcc
	v_cmp_lt_u32_e32 vcc, s35, v104
	v_add_u32_e32 v104, 0x62, v190
	s_nop 0
	v_cndmask_b32_e32 v92, v241, v92, vcc
	v_cmp_lt_u32_e32 vcc, s35, v104
	v_add_u32_e32 v104, 0x42, v190
	s_nop 0
	v_cndmask_b32_e32 v77, v241, v77, vcc
	v_cmp_lt_u32_e32 vcc, s35, v104
	v_add_u32_e32 v104, 0x61, v190
	s_nop 0
	v_cndmask_b32_e32 v93, v241, v93, vcc
	v_cmp_lt_u32_e32 vcc, s35, v104
	v_add_u32_e32 v104, 0x41, v190
	s_nop 0
	v_cndmask_b32_e32 v78, v241, v78, vcc
	v_cmp_lt_u32_e32 vcc, s35, v104
	v_add_u32_e32 v104, 0x60, v190
	s_nop 0
	v_cndmask_b32_e32 v94, v241, v94, vcc
	v_cmp_lt_u32_e32 vcc, s35, v104
	v_add_u32_e32 v104, 64, v190
	s_nop 0
	v_cndmask_b32_e32 v79, v241, v79, vcc
	v_cmp_lt_u32_e32 vcc, s35, v104
	s_nop 1
	v_cndmask_b32_e32 v95, v241, v95, vcc

; __device__ __forceinline__ void partialSM(f32x16& p0, f32x16& p1, float& m_reg, float& mn, float& alpha) {
;     ...
;     if (__builtin_expect(__all((pmax - m_reg) <= THR2), 1)) { mn = m_reg; alpha = 1.f; }
;     else { mn = fmaxf(m_reg, pmax); alpha = __builtin_amdgcn_exp2f(m_reg - mn); m_reg = mn; }
; #pragma unroll
;     for (int r = 0; r < 16; ++r) { p0[r] -= mn; p1[r] -= mn; }
; #pragma unroll
;     for (int r = 0; r < 16; ++r) p0[r] = __builtin_amdgcn_exp2f(p0[r]);
.LBB0_506:
	v_cndmask_b32_e64 v104, v104, v188, s[40:41]
	v_sub_f32_e32 v64, v64, v104
	v_sub_f32_e32 v65, v65, v104
	v_sub_f32_e32 v66, v66, v104
	v_sub_f32_e32 v67, v67, v104
	v_sub_f32_e32 v68, v68, v104
	v_sub_f32_e32 v69, v69, v104
	v_sub_f32_e32 v70, v70, v104
	v_sub_f32_e32 v71, v71, v104
	v_sub_f32_e32 v72, v72, v104
	v_sub_f32_e32 v73, v73, v104
	v_sub_f32_e32 v74, v74, v104
	v_sub_f32_e32 v75, v75, v104
	v_sub_f32_e32 v76, v76, v104
	v_sub_f32_e32 v77, v77, v104
	v_sub_f32_e32 v78, v78, v104
	v_sub_f32_e32 v79, v79, v104
	v_exp_f32_e32 v64, v64
	v_exp_f32_e32 v65, v65
	v_exp_f32_e32 v66, v66
	v_exp_f32_e32 v67, v67
	v_exp_f32_e32 v68, v68
	v_exp_f32_e32 v69, v69
	v_exp_f32_e32 v70, v70
	v_exp_f32_e32 v71, v71
	v_exp_f32_e32 v72, v72
	v_exp_f32_e32 v73, v73
	v_exp_f32_e32 v74, v74
	v_exp_f32_e32 v75, v75
	v_exp_f32_e32 v76, v76
	v_exp_f32_e32 v77, v77
	v_exp_f32_e32 v78, v78
	v_exp_f32_e32 v79, v79
	v_sub_f32_e32 v148, v81, v104
	v_sub_f32_e32 v149, v82, v104
	v_sub_f32_e32 v150, v83, v104
	v_sub_f32_e32 v151, v84, v104
	v_sub_f32_e32 v152, v85, v104
	v_sub_f32_e32 v153, v86, v104
	v_sub_f32_e32 v154, v87, v104
	v_sub_f32_e32 v155, v88, v104
	v_sub_f32_e32 v156, v89, v104
	v_sub_f32_e32 v157, v90, v104
	v_sub_f32_e32 v158, v91, v104
	v_sub_f32_e32 v92, v92, v104
	v_sub_f32_e32 v93, v93, v104
	v_sub_f32_e32 v94, v94, v104
	v_sub_f32_e32 v95, v95, v104
	v_sub_f32_e32 v105, v80, v104
	s_waitcnt lgkmcnt(0)
	s_barrier
; __device__ __forceinline__ void finishSM(f32x16& p0, f32x16& p1, float alpha, float& l_reg, bf16x8& pa0, bf16x8& pa1, bf16x8& pa2, bf16x8& pa3) {
; #pragma unroll
;     for (int r = 0; r < 16; ++r) p1[r] = __builtin_amdgcn_exp2f(p1[r]);
;     float ps = 0;
; #pragma unroll
;     for (int r = 0; r < 16; ++r) ps += p0[r];
; #pragma unroll
;     for (int r = 0; r < 16; ++r) ps += p1[r];
;     { auto rr = __builtin_amdgcn_permlane32_swap(__float_as_uint(ps), __float_as_uint(ps), false, false);
;       ps = __uint_as_float(rr[0]) + __uint_as_float(rr[1]); }
;     l_reg = l_reg * alpha + ps;
;     ...
;     PK4(p0, 0, pa0); PK4(p0, 8, pa1); PK4(p1, 0, pa2); PK4(p1, 8, pa3);
; template <int KB>
; __device__ __forceinline__ void qkt(f32x16& p0, f32x16& p1, const char* K_lds, const float* cb_l, int r32, int hi, qlds_t qL) {
;     { const float* cbt = cb_l + KB * 64 + 4 * hi;
; #pragma unroll
;       for (int g4 = 0; g4 < 4; ++g4) { const f32x4 b0 = *(const f32x4*)(cbt + 8 * g4), b1 = *(const f32x4*)(cbt + 32 + 8 * g4);
; #pragma unroll
;           for (int i = 0; i < 4; ++i) { p0[4 * g4 + i] = b0[i]; p1[4 * g4 + i] = b1[i]; } } }
;     const char* kb[4];
; #pragma unroll
;     for (int dd = 0; dd < 4; ++dd) kb[dd] = K_lds + KB * SHM_K + KSWZ(r32, (dd * 16 + hi * 8) * 2);
; #pragma unroll
;     for (int d0 = 0; d0 < 8; ++d0) { const char* a = kb[d0 & 3] + (d0 >> 2) * 128;
;         bf16x8 b0 = *reinterpret_cast<const bf16x8*>(a);
;         bf16x8 b1 = *reinterpret_cast<const bf16x8*>(a + 32 * 256);
;         const bf16x8 q = qL[d0 * 64];
;         p0 = __builtin_amdgcn_mfma_f32_32x32x16_bf16(b0, q, p0, 0, 0, 0);
;         p1 = __builtin_amdgcn_mfma_f32_32x32x16_bf16(b1, q, p1, 0, 0, 0); }
	ds_read_b128 v[122:125], v187
	ds_read_b128 v[126:129], v187 offset:32
	ds_read_b128 v[106:109], v187 offset:128
	ds_read_b128 v[110:113], v187 offset:160
	ds_read_b128 v[130:133], v187 offset:64
	ds_read_b128 v[114:117], v187 offset:192
	ds_read_b128 v[134:137], v187 offset:96
	ds_read_b128 v[118:121], v187 offset:224
	ds_read_b128 v[80:83], v182 offset:32768
	ds_read_b128 v[84:87], v182 offset:40960
	ds_read_b128 v[88:91], v167
	ds_read_b128 v[228:231], v181 offset:32768
	ds_read_b128 v[232:235], v181 offset:40960
	ds_read_b128 v[242:245], v167 offset:1024
	v_exp_f32_e32 v92, v92
	v_exp_f32_e32 v93, v93
	v_exp_f32_e32 v94, v94
	v_exp_f32_e32 v95, v95
	s_waitcnt lgkmcnt(3)
	v_mfma_f32_32x32x16_bf16 v[122:137], v[80:83], v[88:91], v[122:137]
	v_mfma_f32_32x32x16_bf16 v[106:121], v[84:87], v[88:91], v[106:121]
	ds_read_b128 v[80:83], v180 offset:32768
	ds_read_b128 v[84:87], v180 offset:40960
	ds_read_b128 v[88:91], v167 offset:2048
	s_waitcnt lgkmcnt(3)
	v_mfma_f32_32x32x16_bf16 v[122:137], v[228:231], v[242:245], v[122:137]
	v_mfma_f32_32x32x16_bf16 v[106:121], v[232:235], v[242:245], v[106:121]
	ds_read_b128 v[228:231], v179 offset:32768
	ds_read_b128 v[232:235], v179 offset:40960
	ds_read_b128 v[242:245], v167 offset:3072
	s_waitcnt lgkmcnt(3)
	v_mfma_f32_32x32x16_bf16 v[122:137], v[80:83], v[88:91], v[122:137]
	v_mfma_f32_32x32x16_bf16 v[106:121], v[84:87], v[88:91], v[106:121]
	ds_read_b128 v[80:83], v182 offset:32896
	ds_read_b128 v[84:87], v182 offset:41088
	ds_read_b128 v[88:91], v167 offset:4096
	s_waitcnt lgkmcnt(3)
	v_mfma_f32_32x32x16_bf16 v[122:137], v[228:231], v[242:245], v[122:137]
	v_mfma_f32_32x32x16_bf16 v[106:121], v[232:235], v[242:245], v[106:121]
	ds_read_b128 v[228:231], v181 offset:32896
	ds_read_b128 v[232:235], v181 offset:41088
	ds_read_b128 v[242:245], v167 offset:5120
	s_waitcnt lgkmcnt(3)
	v_mfma_f32_32x32x16_bf16 v[122:137], v[80:83], v[88:91], v[122:137]
	v_mfma_f32_32x32x16_bf16 v[106:121], v[84:87], v[88:91], v[106:121]
	ds_read_b128 v[80:83], v180 offset:32896
	ds_read_b128 v[84:87], v180 offset:41088
	ds_read_b128 v[88:91], v167 offset:6144
	s_waitcnt lgkmcnt(3)
	v_mfma_f32_32x32x16_bf16 v[122:137], v[228:231], v[242:245], v[122:137]
	v_mfma_f32_32x32x16_bf16 v[106:121], v[232:235], v[242:245], v[106:121]
	ds_read_b128 v[228:231], v179 offset:32896
	ds_read_b128 v[232:235], v179 offset:41088
	ds_read_b128 v[242:245], v167 offset:7168
	s_waitcnt lgkmcnt(3)
	v_mfma_f32_32x32x16_bf16 v[122:137], v[80:83], v[88:91], v[122:137]
	v_mfma_f32_32x32x16_bf16 v[106:121], v[84:87], v[88:91], v[106:121]
	s_waitcnt lgkmcnt(0)
	v_mfma_f32_32x32x16_bf16 v[122:137], v[228:231], v[242:245], v[122:137]
	v_exp_f32_e32 v80, v105
	v_add_f32_e32 v105, 0, v64
	v_add_f32_e32 v105, v65, v105
	v_add_f32_e32 v105, v66, v105
	v_add_f32_e32 v105, v67, v105
	v_add_f32_e32 v105, v68, v105
	v_add_f32_e32 v105, v69, v105
	v_add_f32_e32 v105, v70, v105
	v_add_f32_e32 v105, v71, v105
	v_add_f32_e32 v105, v72, v105
	v_add_f32_e32 v105, v73, v105
	v_add_f32_e32 v105, v74, v105
	v_add_f32_e32 v105, v75, v105
	v_add_f32_e32 v105, v76, v105
	v_exp_f32_e32 v81, v148
	v_add_f32_e32 v105, v77, v105
	v_exp_f32_e32 v82, v149
	v_add_f32_e32 v105, v78, v105
	v_exp_f32_e32 v83, v150
	v_add_f32_e32 v105, v79, v105
	v_mfma_f32_32x32x16_bf16 v[106:121], v[232:235], v[242:245], v[106:121]
	v_exp_f32_e32 v84, v151
	v_add_f32_e32 v105, v80, v105
	v_exp_f32_e32 v85, v152
	v_add_f32_e32 v105, v81, v105
	v_exp_f32_e32 v86, v153
	v_add_f32_e32 v105, v82, v105
	v_exp_f32_e32 v87, v154
	v_add_f32_e32 v105, v83, v105
	v_exp_f32_e32 v88, v155
	v_add_f32_e32 v105, v84, v105
	v_exp_f32_e32 v89, v156
	v_add_f32_e32 v105, v85, v105
	v_exp_f32_e32 v90, v157
	v_add_f32_e32 v105, v86, v105
	v_exp_f32_e32 v91, v158
	v_add_f32_e32 v105, v87, v105
	v_add_f32_e32 v105, v88, v105
	v_add_f32_e32 v105, v89, v105
	v_add_f32_e32 v105, v90, v105
	v_add_f32_e32 v105, v91, v105
	v_add_f32_e32 v105, v92, v105
	v_add_f32_e32 v105, v93, v105
	v_add_f32_e32 v105, v94, v105
	v_add_f32_e32 v222, v95, v105
	v_mov_b32_e32 v223, v222
	v_cvt_pk_bf16_f32 v148, v64, v65
	v_cvt_pk_bf16_f32 v149, v66, v67
	v_cvt_pk_bf16_f32 v150, v68, v69
	v_cvt_pk_bf16_f32 v151, v70, v71
	v_cvt_pk_bf16_f32 v152, v72, v73
	v_cvt_pk_bf16_f32 v153, v74, v75
	v_cvt_pk_bf16_f32 v154, v76, v77
	v_cvt_pk_bf16_f32 v155, v78, v79
	v_cvt_pk_bf16_f32 v160, v80, v81
	v_cvt_pk_bf16_f32 v161, v82, v83
	v_cvt_pk_bf16_f32 v162, v84, v85
	v_cvt_pk_bf16_f32 v163, v86, v87
	v_cvt_pk_bf16_f32 v156, v88, v89
	v_cvt_pk_bf16_f32 v157, v90, v91
	v_cvt_pk_bf16_f32 v158, v92, v93
	v_cvt_pk_bf16_f32 v159, v94, v95
	s_nop 1
	v_permlane32_swap_b32_e32 v222, v223
	v_permlane32_swap_b32_e32 v148, v150
	v_permlane32_swap_b32_e32 v149, v151
	v_permlane32_swap_b32_e32 v152, v154
	v_permlane32_swap_b32_e32 v153, v155
	v_permlane32_swap_b32_e32 v160, v162
	v_permlane32_swap_b32_e32 v161, v163
	v_permlane32_swap_b32_e32 v156, v158
	v_permlane32_swap_b32_e32 v157, v159
	s_add_i32 s6, s12, 1
	s_cmp_lt_i32 s6, s93
	s_cselect_b64 s[56:57], -1, 0
	s_cmp_ge_i32 s6, s93
	s_cbranch_scc1 .LBB0_508
	s_add_i32 s40, s13, 0x41
	s_ashr_i32 s41, s40, 31
	s_lshl_b64 vcc, s[40:41], 8
	s_add_u32 s42, s48, vcc_lo
	s_addc_u32 s43, s49, vcc_hi
	s_add_u32 s6, s46, vcc_lo
	v_lshl_add_u64 v[96:97], s[42:43], 0, v[138:139]
	s_addc_u32 s7, s47, vcc_hi
	v_add_co_u32_e32 v100, vcc, s60, v96
	v_lshl_add_u64 v[140:141], s[6:7], 0, v[138:139]
	s_nop 0
	v_addc_co_u32_e32 v101, vcc, 0, v97, vcc
	v_add_co_u32_e32 v144, vcc, 0x2000, v140
	v_lshl_add_u64 v[198:199], s[40:41], 2, v[168:169]
	s_nop 0
	v_addc_co_u32_e32 v145, vcc, 0, v141, vcc
	global_load_dwordx4 v[96:99], v[96:97], off
	s_nop 0
	global_load_dwordx4 v[100:103], v[100:101], off
	s_nop 0
	global_load_dwordx4 v[140:143], v[140:141], off
	s_nop 0
	global_load_dwordx4 v[144:147], v[144:145], off
	s_nop 0
	global_load_dword v207, v[198:199], off
